# v113 + P0 RMSNorm row loop: all 8 norm-weight chunks loaded at the top of the row, store ladder uses counted waits instead of vmcnt(0) per chunk
# speedup vs baseline: 1.0065x; 1.0065x over previous
.LBB0_158:
	s_cmpk_gt_i32 s24, 0x1fff
	s_mov_b64 s[14:15], -1
	s_cbranch_scc0 .LBB0_160
	s_add_i32 s12, s24, 0xffffe000
	s_lshl_b64 s[0:1], s[12:13], 13
	v_lshl_add_u64 v[2:3], v[28:29], 0, s[0:1]
	global_load_dwordx4 v[62:65], v[2:3], off nt
	global_load_dwordx4 v[22:25], v[2:3], off offset:1024 nt
	global_load_dwordx4 v[66:69], v[2:3], off offset:2048 nt
	global_load_dwordx4 v[18:21], v[2:3], off offset:3072 nt
	v_add_co_u32_e32 v70, vcc, s2, v2
	s_mov_b32 s25, s13
	s_nop 0
	v_addc_co_u32_e32 v71, vcc, 0, v3, vcc
	global_load_dwordx4 v[6:9], v[70:71], off nt
	global_load_dwordx4 v[14:17], v[70:71], off offset:1024 nt
	global_load_dwordx4 v[2:5], v[70:71], off offset:3072 nt
	global_load_dwordx4 v[10:13], v[70:71], off offset:2048 nt
	v_cmp_lt_i32_e32 vcc, v54, v53
	global_load_dwordx4 v[70:73], v[30:31], off
	global_load_dwordx4 v[108:111], v[30:31], off offset:1024
	global_load_dwordx4 v[112:115], v[30:31], off offset:2048
	global_load_dwordx4 v[116:119], v[30:31], off offset:3072
	global_load_dwordx4 v[120:123], v[32:33], off
	global_load_dwordx4 v[124:127], v[34:35], off
	global_load_dwordx4 v[128:131], v[36:37], off
	global_load_dwordx4 v[132:135], v[38:39], off
	s_lshl_b64 s[0:1], s[24:25], 12
	v_cndmask_b32_e32 v61, v52, v54, vcc
	v_lshlrev_b32_e32 v61, 2, v61
	v_cmp_lt_i32_e32 vcc, v55, v53
	s_add_u32 s0, s56, s0
	s_addc_u32 s1, s57, s1
	s_mov_b64 s[14:15], 0
	s_waitcnt vmcnt(15)
	v_mov_b32_e32 v76, v63
	s_waitcnt vmcnt(14)
	v_mov_b32_e32 v77, v23
	v_mov_b32_e32 v80, v65
	v_mov_b32_e32 v81, v25
	v_mov_b32_e32 v74, v62
	v_mov_b32_e32 v75, v22
	v_mov_b32_e32 v78, v64
	v_mov_b32_e32 v79, v24
	s_waitcnt vmcnt(13)
	v_pk_mul_f32 v[82:83], v[68:69], v[68:69]
	v_pk_mul_f32 v[84:85], v[66:67], v[66:67]
	v_pk_mul_f32 v[76:77], v[76:77], v[76:77]
	v_pk_mul_f32 v[80:81], v[80:81], v[80:81]
	v_pk_mov_b32 v[90:91], v[84:85], v[82:83] op_sel:[1,0]
	v_mov_b32_e32 v85, v83
	v_pk_fma_f32 v[74:75], v[74:75], v[74:75], v[76:77]
	v_pk_fma_f32 v[76:77], v[78:79], v[78:79], v[80:81]
	s_waitcnt vmcnt(12)
	v_mul_f32_e32 v86, v19, v19
	v_mul_f32_e32 v88, v21, v21
	v_pk_add_f32 v[78:79], v[90:91], v[84:85]
	v_pk_add_f32 v[74:75], v[74:75], v[76:77]
	s_waitcnt vmcnt(11)
	v_mul_f32_e32 v95, v6, v6
	v_mul_f32_e32 v97, v7, v7
	v_mul_f32_e32 v98, v8, v8
	v_mul_f32_e32 v99, v9, v9
	v_pk_fma_f32 v[82:83], v[18:19], v[18:19], v[86:87] op_sel_hi:[1,1,0]
	v_pk_fma_f32 v[86:87], v[20:21], v[20:21], v[88:89] op_sel_hi:[1,1,0]
	v_pk_add_f32 v[76:77], v[78:79], v[78:79] op_sel:[0,1] op_sel_hi:[1,0]
	v_pk_add_f32 v[74:75], v[74:75], v[74:75] op_sel:[0,1] op_sel_hi:[1,0]
	s_waitcnt vmcnt(10)
	v_pk_mul_f32 v[88:89], v[16:17], v[16:17]
	v_pk_mul_f32 v[92:93], v[14:15], v[14:15]
	v_mov_b32_e32 v83, v98
	v_mov_b32_e32 v87, v99
	v_mov_b32_e32 v77, v97
	v_mov_b32_e32 v75, v95
	v_pk_mov_b32 v[80:81], v[92:93], v[88:89] op_sel:[1,0]
	v_mov_b32_e32 v93, v89
	v_pk_add_f32 v[78:79], v[82:83], v[86:87]
	v_pk_add_f32 v[74:75], v[74:75], v[76:77]
	s_waitcnt vmcnt(8)
	v_mul_f32_e32 v94, v11, v11
	v_mul_f32_e32 v96, v13, v13
	v_pk_add_f32 v[80:81], v[80:81], v[92:93]
	v_pk_add_f32 v[74:75], v[74:75], v[78:79]
	v_mul_f32_e32 v100, v2, v2
	v_mul_f32_e32 v101, v3, v3
	v_mul_f32_e32 v102, v4, v4
	v_mul_f32_e32 v103, v5, v5
	v_pk_fma_f32 v[84:85], v[10:11], v[10:11], v[94:95] op_sel_hi:[1,1,0]
	v_pk_fma_f32 v[88:89], v[12:13], v[12:13], v[96:97] op_sel_hi:[1,1,0]
	v_pk_add_f32 v[80:81], v[80:81], v[80:81] op_sel:[0,1] op_sel_hi:[1,0]
	v_pk_add_f32 v[74:75], v[74:75], v[74:75] op_sel:[0,1] op_sel_hi:[1,0]
	v_mov_b32_e32 v85, v102
	v_mov_b32_e32 v89, v103
	v_mov_b32_e32 v81, v101
	v_mov_b32_e32 v75, v100
	v_pk_add_f32 v[82:83], v[84:85], v[88:89]
	v_pk_add_f32 v[74:75], v[74:75], v[80:81]
	s_nop 0
	v_pk_add_f32 v[74:75], v[74:75], v[82:83]
	s_nop 0
	v_add_f32_e32 v74, v74, v75
	ds_bpermute_b32 v61, v61, v74
	v_cndmask_b32_e32 v75, v52, v55, vcc
	v_lshlrev_b32_e32 v75, 2, v75
	v_cmp_lt_i32_e32 vcc, v56, v53
	s_waitcnt lgkmcnt(0)
	v_add_f32_e32 v61, v74, v61
	ds_bpermute_b32 v74, v75, v61
	v_cndmask_b32_e32 v75, v52, v56, vcc
	v_lshlrev_b32_e32 v75, 2, v75
	v_cmp_lt_i32_e32 vcc, v57, v53
	s_waitcnt lgkmcnt(0)
	v_add_f32_e32 v61, v61, v74
	ds_bpermute_b32 v74, v75, v61
	v_cndmask_b32_e32 v75, v52, v57, vcc
	v_lshlrev_b32_e32 v75, 2, v75
	v_cmp_lt_i32_e32 vcc, v58, v53
	s_waitcnt lgkmcnt(0)
	v_add_f32_e32 v61, v61, v74
	ds_bpermute_b32 v74, v75, v61
	v_cndmask_b32_e32 v75, v52, v58, vcc
	v_lshlrev_b32_e32 v75, 2, v75
	v_cmp_lt_i32_e32 vcc, v59, v53
	s_waitcnt lgkmcnt(0)
	v_add_f32_e32 v61, v61, v74
	ds_bpermute_b32 v74, v75, v61
	v_cndmask_b32_e32 v75, v52, v59, vcc
	v_lshlrev_b32_e32 v75, 2, v75
	s_waitcnt lgkmcnt(0)
	v_add_f32_e32 v61, v61, v74
	ds_bpermute_b32 v74, v75, v61
	s_waitcnt lgkmcnt(0)
	v_add_f32_e32 v61, v61, v74
	v_fmamk_f32 v61, v61, 0x3a000000, v1
	v_mul_f32_e32 v74, 0x4b800000, v61
	v_cmp_gt_f32_e32 vcc, s3, v61
	s_nop 1
	v_cndmask_b32_e32 v61, v61, v74, vcc
	v_rsq_f32_e32 v61, v61
	s_nop 0
	v_mul_f32_e32 v74, 0x45800000, v61
	v_cndmask_b32_e32 v74, v61, v74, vcc
	v_pk_mul_f32 v[62:63], v[62:63], v[74:75] op_sel_hi:[1,0]
	v_pk_mul_f32 v[64:65], v[64:65], v[74:75] op_sel_hi:[1,0]
	s_waitcnt vmcnt(7)
	v_pk_mul_f32 v[62:63], v[70:71], v[62:63]
	v_pk_mul_f32 v[64:65], v[72:73], v[64:65]
	v_cvt_pk_bf16_f32 v62, v62, v63
	v_pk_mul_f32 v[22:23], v[22:23], v[74:75] op_sel_hi:[1,0]
	v_cvt_pk_bf16_f32 v63, v64, v65
	global_store_dwordx2 v60, v[62:63], s[0:1]
	v_pk_mul_f32 v[24:25], v[24:25], v[74:75] op_sel_hi:[1,0]
	v_pk_mul_f32 v[18:19], v[18:19], v[74:75] op_sel_hi:[1,0]
	v_pk_mul_f32 v[20:21], v[20:21], v[74:75] op_sel_hi:[1,0]
	v_pk_mul_f32 v[6:7], v[6:7], v[74:75] op_sel_hi:[1,0]
	v_pk_mul_f32 v[8:9], v[8:9], v[74:75] op_sel_hi:[1,0]
	v_pk_mul_f32 v[14:15], v[14:15], v[74:75] op_sel_hi:[1,0]
	v_pk_mul_f32 v[16:17], v[16:17], v[74:75] op_sel_hi:[1,0]
	v_pk_mul_f32 v[10:11], v[10:11], v[74:75] op_sel_hi:[1,0]
	v_pk_mul_f32 v[12:13], v[12:13], v[74:75] op_sel_hi:[1,0]
	v_pk_mul_f32 v[2:3], v[2:3], v[74:75] op_sel_hi:[1,0]
	v_pk_mul_f32 v[4:5], v[4:5], v[74:75] op_sel_hi:[1,0]
	s_waitcnt vmcnt(7)
	v_pk_mul_f32 v[22:23], v[108:109], v[22:23]
	v_pk_mul_f32 v[24:25], v[110:111], v[24:25]
	v_cvt_pk_bf16_f32 v22, v22, v23
	v_pk_mul_f32 v[62:63], v[66:67], v[74:75] op_sel_hi:[1,0]
	v_cvt_pk_bf16_f32 v23, v24, v25
	global_store_dwordx2 v60, v[22:23], s[0:1] offset:512
	v_pk_mul_f32 v[64:65], v[68:69], v[74:75] op_sel_hi:[1,0]
	s_waitcnt vmcnt(7)
	v_pk_mul_f32 v[22:23], v[112:113], v[62:63]
	v_pk_mul_f32 v[24:25], v[114:115], v[64:65]
	v_cvt_pk_bf16_f32 v22, v22, v23
	s_nop 0
	v_cvt_pk_bf16_f32 v23, v24, v25
	global_store_dwordx2 v60, v[22:23], s[0:1] offset:1024
	s_waitcnt vmcnt(7)
	v_pk_mul_f32 v[18:19], v[18:19], v[116:117]
	v_pk_mul_f32 v[20:21], v[20:21], v[118:119]
	v_cvt_pk_bf16_f32 v18, v18, v19
	s_nop 0
	v_cvt_pk_bf16_f32 v19, v20, v21
	global_store_dwordx2 v60, v[18:19], s[0:1] offset:1536
	s_waitcnt vmcnt(7)
	v_pk_mul_f32 v[6:7], v[6:7], v[120:121]
	v_pk_mul_f32 v[8:9], v[8:9], v[122:123]
	v_cvt_pk_bf16_f32 v6, v6, v7
	s_nop 0
	v_cvt_pk_bf16_f32 v7, v8, v9
	global_store_dwordx2 v60, v[6:7], s[0:1] offset:2048
	s_waitcnt vmcnt(7)
	v_pk_mul_f32 v[6:7], v[14:15], v[124:125]
	v_pk_mul_f32 v[8:9], v[16:17], v[126:127]
	v_cvt_pk_bf16_f32 v6, v6, v7
	s_nop 0
	v_cvt_pk_bf16_f32 v7, v8, v9
	global_store_dwordx2 v60, v[6:7], s[0:1] offset:2560
	s_waitcnt vmcnt(7)
	v_pk_mul_f32 v[6:7], v[10:11], v[128:129]
	v_pk_mul_f32 v[8:9], v[12:13], v[130:131]
	v_cvt_pk_bf16_f32 v6, v6, v7
	s_nop 0
	v_cvt_pk_bf16_f32 v7, v8, v9
	global_store_dwordx2 v60, v[6:7], s[0:1] offset:3072
	s_waitcnt vmcnt(7)
	v_pk_mul_f32 v[2:3], v[2:3], v[132:133]
	v_pk_mul_f32 v[4:5], v[4:5], v[134:135]
	v_cvt_pk_bf16_f32 v2, v2, v3
	s_nop 0
	v_cvt_pk_bf16_f32 v3, v4, v5
.LBB0_160:
	s_andn2_b64 vcc, exec, s[14:15]
	s_cbranch_vccnz .LBB0_157
	global_load_dwordx4 v[62:65], v[50:51], off offset:-4096 nt
	global_load_dwordx4 v[18:21], v[50:51], off offset:-3072 nt
	global_load_dwordx4 v[66:69], v[50:51], off offset:-2048 nt
	global_load_dwordx4 v[6:9], v[50:51], off nt
	global_load_dwordx4 v[22:25], v[50:51], off offset:-1024 nt
	global_load_dwordx4 v[14:17], v[50:51], off offset:1024 nt
	global_load_dwordx4 v[2:5], v[50:51], off offset:3072 nt
	global_load_dwordx4 v[10:13], v[50:51], off offset:2048 nt
	global_load_dwordx4 v[70:73], v[40:41], off
	global_load_dwordx4 v[108:111], v[40:41], off offset:1024
	global_load_dwordx4 v[112:115], v[40:41], off offset:2048
	global_load_dwordx4 v[116:119], v[40:41], off offset:3072
	global_load_dwordx4 v[120:123], v[42:43], off
	global_load_dwordx4 v[124:127], v[44:45], off
	global_load_dwordx4 v[128:131], v[46:47], off
	global_load_dwordx4 v[132:135], v[48:49], off
	v_cmp_lt_i32_e32 vcc, v54, v53
	s_waitcnt vmcnt(15)
	v_mov_b32_e32 v76, v63
	s_waitcnt vmcnt(14)
	v_mov_b32_e32 v77, v19
	v_mov_b32_e32 v80, v65
	v_mov_b32_e32 v81, v21
	v_mov_b32_e32 v74, v62
	v_mov_b32_e32 v75, v18
	v_mov_b32_e32 v78, v64
	v_mov_b32_e32 v79, v20
	s_waitcnt vmcnt(13)
	v_pk_mul_f32 v[82:83], v[68:69], v[68:69]
	v_pk_mul_f32 v[84:85], v[66:67], v[66:67]
	v_pk_mul_f32 v[76:77], v[76:77], v[76:77]
	v_pk_mul_f32 v[80:81], v[80:81], v[80:81]
	v_pk_mov_b32 v[98:99], v[84:85], v[82:83] op_sel:[1,0]
	v_mov_b32_e32 v85, v83
	v_pk_fma_f32 v[74:75], v[74:75], v[74:75], v[76:77]
	v_pk_fma_f32 v[76:77], v[78:79], v[78:79], v[80:81]
	s_waitcnt vmcnt(11)
	v_mul_f32_e32 v86, v23, v23
	v_mul_f32_e32 v88, v25, v25
	v_pk_add_f32 v[78:79], v[98:99], v[84:85]
	v_pk_add_f32 v[74:75], v[74:75], v[76:77]
	v_mul_f32_e32 v97, v6, v6
	v_mul_f32_e32 v100, v7, v7
	v_mul_f32_e32 v101, v8, v8
	v_mul_f32_e32 v102, v9, v9
	v_pk_fma_f32 v[82:83], v[22:23], v[22:23], v[86:87] op_sel_hi:[1,1,0]
	v_pk_fma_f32 v[86:87], v[24:25], v[24:25], v[88:89] op_sel_hi:[1,1,0]
	v_pk_add_f32 v[76:77], v[78:79], v[78:79] op_sel:[0,1] op_sel_hi:[1,0]
	v_pk_add_f32 v[74:75], v[74:75], v[74:75] op_sel:[0,1] op_sel_hi:[1,0]
	s_waitcnt vmcnt(10)
	v_pk_mul_f32 v[90:91], v[16:17], v[16:17]
	v_pk_mul_f32 v[92:93], v[14:15], v[14:15]
	v_mov_b32_e32 v83, v101
	v_mov_b32_e32 v87, v102
	v_mov_b32_e32 v77, v100
	v_mov_b32_e32 v75, v97
	v_pk_mov_b32 v[88:89], v[92:93], v[90:91] op_sel:[1,0]
	v_mov_b32_e32 v93, v91
	v_pk_add_f32 v[78:79], v[82:83], v[86:87]
	v_pk_add_f32 v[74:75], v[74:75], v[76:77]
	s_waitcnt vmcnt(8)
	v_mul_f32_e32 v94, v11, v11
	v_mul_f32_e32 v96, v13, v13
	v_pk_add_f32 v[80:81], v[88:89], v[92:93]
	v_pk_add_f32 v[74:75], v[74:75], v[78:79]
	v_mul_f32_e32 v103, v2, v2
	v_mul_f32_e32 v104, v3, v3
	v_mul_f32_e32 v105, v4, v4
	v_mul_f32_e32 v106, v5, v5
	v_pk_fma_f32 v[90:91], v[10:11], v[10:11], v[94:95] op_sel_hi:[1,1,0]
	v_pk_fma_f32 v[94:95], v[12:13], v[12:13], v[96:97] op_sel_hi:[1,1,0]
	v_pk_add_f32 v[80:81], v[80:81], v[80:81] op_sel:[0,1] op_sel_hi:[1,0]
	v_pk_add_f32 v[74:75], v[74:75], v[74:75] op_sel:[0,1] op_sel_hi:[1,0]
	v_mov_b32_e32 v91, v105
	v_mov_b32_e32 v95, v106
	v_mov_b32_e32 v81, v104
	v_mov_b32_e32 v75, v103
	v_pk_add_f32 v[82:83], v[90:91], v[94:95]
	v_pk_add_f32 v[74:75], v[74:75], v[80:81]
	v_cndmask_b32_e32 v61, v52, v54, vcc
	v_pk_add_f32 v[74:75], v[74:75], v[82:83]
	v_lshlrev_b32_e32 v61, 2, v61
	v_add_f32_e32 v74, v74, v75
	ds_bpermute_b32 v61, v61, v74
	v_cmp_lt_i32_e32 vcc, v55, v53
	s_waitcnt lgkmcnt(0)
	v_add_f32_e32 v61, v74, v61
	v_cndmask_b32_e32 v75, v52, v55, vcc
	v_lshlrev_b32_e32 v75, 2, v75
	ds_bpermute_b32 v74, v75, v61
	v_cmp_lt_i32_e32 vcc, v56, v53
	s_waitcnt lgkmcnt(0)
	v_add_f32_e32 v61, v61, v74
	v_cndmask_b32_e32 v75, v52, v56, vcc
	v_lshlrev_b32_e32 v75, 2, v75
	ds_bpermute_b32 v74, v75, v61
	v_cmp_lt_i32_e32 vcc, v57, v53
	s_waitcnt lgkmcnt(0)
	v_add_f32_e32 v61, v61, v74
	v_cndmask_b32_e32 v75, v52, v57, vcc
	v_lshlrev_b32_e32 v75, 2, v75
	ds_bpermute_b32 v74, v75, v61
	v_cmp_lt_i32_e32 vcc, v58, v53
	s_waitcnt lgkmcnt(0)
	v_add_f32_e32 v61, v61, v74
	v_cndmask_b32_e32 v75, v52, v58, vcc
	v_lshlrev_b32_e32 v75, 2, v75
	ds_bpermute_b32 v74, v75, v61
	v_cmp_lt_i32_e32 vcc, v59, v53
	s_waitcnt lgkmcnt(0)
	v_add_f32_e32 v61, v61, v74
	v_cndmask_b32_e32 v75, v52, v59, vcc
	v_lshlrev_b32_e32 v75, 2, v75
	ds_bpermute_b32 v76, v75, v61
	v_lshl_add_u64 v[74:75], s[8:9], 0, v[26:27]
	v_add_co_u32_e64 v74, s[0:1], s16, v74
	s_waitcnt lgkmcnt(0)
	v_add_f32_e32 v61, v61, v76
	v_fmamk_f32 v61, v61, 0x3a000000, v1
	v_mul_f32_e32 v76, 0x4b800000, v61
	v_cmp_gt_f32_e32 vcc, s3, v61
	v_addc_co_u32_e64 v75, s[0:1], 0, v75, s[0:1]
	s_nop 0
	v_cndmask_b32_e32 v61, v61, v76, vcc
	v_rsq_f32_e32 v61, v61
	s_add_u32 s0, s8, 0x8c00000
	s_addc_u32 s1, s9, 0
	v_mul_f32_e32 v76, 0x45800000, v61
	v_cndmask_b32_e32 v76, v61, v76, vcc
	v_pk_mul_f32 v[62:63], v[62:63], v[76:77] op_sel_hi:[1,0]
	v_pk_mul_f32 v[64:65], v[64:65], v[76:77] op_sel_hi:[1,0]
	s_waitcnt vmcnt(7)
	v_pk_mul_f32 v[62:63], v[70:71], v[62:63]
	v_pk_mul_f32 v[64:65], v[72:73], v[64:65]
	v_cvt_pk_bf16_f32 v62, v62, v63
	v_pk_mul_f32 v[18:19], v[18:19], v[76:77] op_sel_hi:[1,0]
	v_cvt_pk_bf16_f32 v63, v64, v65
	global_store_dwordx2 v[74:75], v[62:63], off
	v_pk_mul_f32 v[20:21], v[20:21], v[76:77] op_sel_hi:[1,0]
	v_pk_mul_f32 v[22:23], v[22:23], v[76:77] op_sel_hi:[1,0]
	v_pk_mul_f32 v[24:25], v[24:25], v[76:77] op_sel_hi:[1,0]
	v_pk_mul_f32 v[6:7], v[6:7], v[76:77] op_sel_hi:[1,0]
	v_pk_mul_f32 v[8:9], v[8:9], v[76:77] op_sel_hi:[1,0]
	v_pk_mul_f32 v[14:15], v[14:15], v[76:77] op_sel_hi:[1,0]
	v_pk_mul_f32 v[16:17], v[16:17], v[76:77] op_sel_hi:[1,0]
	v_pk_mul_f32 v[10:11], v[10:11], v[76:77] op_sel_hi:[1,0]
	v_pk_mul_f32 v[12:13], v[12:13], v[76:77] op_sel_hi:[1,0]
	v_pk_mul_f32 v[2:3], v[2:3], v[76:77] op_sel_hi:[1,0]
	v_pk_mul_f32 v[4:5], v[4:5], v[76:77] op_sel_hi:[1,0]
	s_waitcnt vmcnt(7)
	v_pk_mul_f32 v[18:19], v[108:109], v[18:19]
	v_pk_mul_f32 v[20:21], v[110:111], v[20:21]
	v_cvt_pk_bf16_f32 v18, v18, v19
	v_pk_mul_f32 v[62:63], v[66:67], v[76:77] op_sel_hi:[1,0]
	v_cvt_pk_bf16_f32 v19, v20, v21
	global_store_dwordx2 v[74:75], v[18:19], off offset:512
	v_pk_mul_f32 v[64:65], v[68:69], v[76:77] op_sel_hi:[1,0]
	s_waitcnt vmcnt(7)
	v_pk_mul_f32 v[18:19], v[112:113], v[62:63]
	v_pk_mul_f32 v[20:21], v[114:115], v[64:65]
	v_cvt_pk_bf16_f32 v18, v18, v19
	s_nop 0
	v_cvt_pk_bf16_f32 v19, v20, v21
	global_store_dwordx2 v[74:75], v[18:19], off offset:1024
	s_waitcnt vmcnt(7)
	v_pk_mul_f32 v[18:19], v[22:23], v[116:117]
	v_pk_mul_f32 v[20:21], v[24:25], v[118:119]
	v_cvt_pk_bf16_f32 v18, v18, v19
	s_nop 0
	v_cvt_pk_bf16_f32 v19, v20, v21
	global_store_dwordx2 v[74:75], v[18:19], off offset:1536
	s_waitcnt vmcnt(7)
	v_pk_mul_f32 v[6:7], v[6:7], v[120:121]
	v_pk_mul_f32 v[8:9], v[8:9], v[122:123]
	v_cvt_pk_bf16_f32 v6, v6, v7
	s_nop 0
	v_cvt_pk_bf16_f32 v7, v8, v9
	global_store_dwordx2 v[74:75], v[6:7], off offset:2048
	s_waitcnt vmcnt(7)
	v_pk_mul_f32 v[6:7], v[14:15], v[124:125]
	v_pk_mul_f32 v[8:9], v[16:17], v[126:127]
	v_cvt_pk_bf16_f32 v6, v6, v7
	s_nop 0
	v_cvt_pk_bf16_f32 v7, v8, v9
	global_store_dwordx2 v[74:75], v[6:7], off offset:2560
	s_waitcnt vmcnt(7)
	v_pk_mul_f32 v[6:7], v[10:11], v[128:129]
	v_pk_mul_f32 v[8:9], v[12:13], v[130:131]
	v_cvt_pk_bf16_f32 v6, v6, v7
	s_nop 0
	v_cvt_pk_bf16_f32 v7, v8, v9
	global_store_dwordx2 v[74:75], v[6:7], off offset:3072
	s_waitcnt vmcnt(7)
	v_pk_mul_f32 v[2:3], v[2:3], v[132:133]
	v_pk_mul_f32 v[4:5], v[4:5], v[134:135]
	v_cvt_pk_bf16_f32 v2, v2, v3
	s_nop 0
	v_cvt_pk_bf16_f32 v3, v4, v5
	s_branch .LBB0_157
